# SWA attention: the epilogue's sink and gate-row loads are requested at the start of the item (before the K/V tile loop) into free registers
# baseline (speedup 1.0000x reference)
.LBB0_2135:
	s_load_dwordx2 s[82:83], s[0:1], 0x68
	s_load_dwordx2 s[86:87], s[0:1], 0x160
	v_bfe_u32 v178, v91, 3, 3
	v_lshlrev_b32_e32 v178, 11, v178
	v_and_b32_e32 v179, 7, v91
	v_lshl_or_b32 v178, v179, 4, v178
	v_mov_b32_e32 v177, 0
	v_and_b32_e32 v3, 64, v91
	s_load_dwordx4 s[4:7], s[0:1], 0x190
	s_load_dwordx2 s[12:13], s[0:1], 0x1a0
	v_xor_b32_e32 v2, 32, v91
	v_add_u32_e32 v3, 64, v3
	v_and_b32_e32 v90, 31, v0
	v_lshrrev_b32_e32 v0, 2, v0
	v_cmp_lt_i32_e32 vcc, v2, v3
	v_mov_b32_e32 v1, 0
	v_and_b32_e32 v0, 8, v0
	v_cndmask_b32_e32 v2, v91, v2, vcc
	s_ashr_i32 s25, s2, 6
	v_lshlrev_b32_e32 v98, 2, v2
	s_lshl_b32 s26, s24, 5
	s_lshl_b32 s27, s42, 5
	v_mov_b32_e32 v99, 0x7f
	v_lshlrev_b32_e32 v92, 1, v0
	s_mov_b32 s15, 0
	v_mov_b32_e32 v93, v1
	s_movk_i32 s28, 0x90
	s_movk_i32 s29, 0xc0
	s_mov_b32 s30, 0xff800000
	s_mov_b32 s31, 0x3fb8aa3b
	s_mov_b32 s34, 0x5040100
	v_mov_b32_e32 v100, 0xff800000
	s_branch .LBB0_2137
.LBB0_2136:
	s_load_dwordx2 s[2:3], s[0:1], 0x68
	s_load_dwordx4 s[8:11], s[0:1], 0x158
	s_ashr_i32 s21, s20, 31
	s_lshl_b64 s[20:21], s[20:21], 2
	v_mov_b32_e32 v4, v91
	s_waitcnt lgkmcnt(0)
	s_add_u32 s2, s2, s20
	s_addc_u32 s3, s3, s21
	s_waitcnt vmcnt(0)
	v_mov_b32_e32 v0, v176
	v_mov_b32_e32 v53, s17
	v_lshlrev_b32_e32 v12, 3, v4
	v_bfe_u32 v15, v4, 3, 3
	v_and_b32_e32 v16, 56, v12
	v_or_b32_e32 v52, s16, v15
	v_mov_b32_e32 v51, s19
	v_mov_b32_e32 v55, s17
	v_or_b32_e32 v50, s18, v16
	v_lshlrev_b64 v[56:57], 10, v[52:53]
	v_or_b32_e32 v54, 8, v52
	v_lshl_add_u64 v[56:57], v[56:57], 0, v[50:51]
	v_lshlrev_b64 v[54:55], 10, v[54:55]
	v_lshlrev_b64 v[62:63], 1, v[56:57]
	v_lshl_add_u64 v[54:55], v[54:55], 0, v[50:51]
	v_lshl_add_u64 v[64:65], s[10:11], 0, v[62:63]
	s_waitcnt vmcnt(2)
	v_lshlrev_b64 v[66:67], 1, v[54:55]
	v_lshl_add_u64 v[68:69], s[10:11], 0, v[66:67]
	v_mov_b32_e32 v54, v160
	v_mov_b32_e32 v55, v161
	v_mov_b32_e32 v56, v162
	v_mov_b32_e32 v57, v163
	v_mov_b32_e32 v58, v164
	v_mov_b32_e32 v59, v165
	v_mov_b32_e32 v60, v166
	v_mov_b32_e32 v61, v167
	ds_bpermute_b32 v3, v98, v101
	v_add_u32_e32 v7, s70, v4
	v_and_b32_e32 v8, 31, v4
	v_readfirstlane_b32 s2, v7
	s_lshr_b32 s2, s2, 6
	s_mulk_i32 s2, 0x1200
	s_waitcnt lgkmcnt(0)
	v_add_f32_e32 v3, v101, v3
	s_add_i32 s14, s2, 0x18000
	v_lshrrev_b32_e32 v11, 2, v4
	v_mov_b32_e32 v4, s14
	v_mad_u32_u24 v4, v8, s28, v4
	v_and_or_b32 v20, v11, 8, v4
	s_add_i32 s24, s24, s42
	s_add_i32 s26, s26, s27
	s_cmpk_lt_i32 s24, 0x800
	s_waitcnt vmcnt(2)
	v_fma_f32 v0, v0, s31, -v105
	v_exp_f32_e32 v0, v0
	s_nop 0
	v_add_f32_e32 v0, v3, v0
	v_div_scale_f32 v3, s[2:3], v0, v0, 1.0
	v_rcp_f32_e32 v4, v3
	v_div_scale_f32 v7, vcc, 1.0, v0, 1.0
	v_fma_f32 v8, -v3, v4, 1.0
	v_fmac_f32_e32 v4, v8, v4
	v_mul_f32_e32 v8, v7, v4
	v_fma_f32 v11, -v3, v8, v7
	v_fmac_f32_e32 v8, v11, v4
	v_fma_f32 v3, -v3, v8, v7
	v_div_fmas_f32 v3, v3, v4, v8
	v_div_fixup_f32 v0, v3, v0, 1.0
	v_mul_f32_e32 v19, v2, v0
	v_pk_mul_f32 v[2:3], v[48:49], v[0:1] op_sel_hi:[1,0]
	v_mul_f32_e32 v23, v5, v0
	v_mul_f32_e32 v24, v6, v0
	v_pk_mul_f32 v[4:5], v[46:47], v[0:1] op_sel_hi:[1,0]
	v_mul_f32_e32 v27, v9, v0
	v_mul_f32_e32 v28, v10, v0
	v_pk_mul_f32 v[6:7], v[44:45], v[0:1] op_sel_hi:[1,0]
	v_mul_f32_e32 v31, v13, v0
	v_mul_f32_e32 v14, v14, v0
	v_pk_mul_f32 v[8:9], v[42:43], v[0:1] op_sel_hi:[1,0]
	v_mul_f32_e32 v17, v17, v0
	v_mul_f32_e32 v18, v18, v0
	v_pk_mul_f32 v[10:11], v[40:41], v[0:1] op_sel_hi:[1,0]
	v_mul_f32_e32 v21, v21, v0
	v_mul_f32_e32 v22, v22, v0
	v_pk_mul_f32 v[12:13], v[38:39], v[0:1] op_sel_hi:[1,0]
	v_mul_f32_e32 v25, v25, v0
	v_cvt_pk_bf16_f32 v19, v19, s0
	v_cvt_pk_bf16_f32 v3, v2, v3
	v_cvt_pk_bf16_f32 v23, v23, s0
	v_cvt_pk_bf16_f32 v24, v24, s0
	v_cvt_pk_bf16_f32 v5, v4, v5
	v_cvt_pk_bf16_f32 v27, v27, s0
	v_cvt_pk_bf16_f32 v28, v28, s0
	v_cvt_pk_bf16_f32 v7, v6, v7
	v_cvt_pk_bf16_f32 v31, v31, s0
	v_cvt_pk_bf16_f32 v14, v14, s0
	v_cvt_pk_bf16_f32 v9, v8, v9
	v_cvt_pk_bf16_f32 v17, v17, s0
	v_cvt_pk_bf16_f32 v18, v18, s0
	v_cvt_pk_bf16_f32 v11, v10, v11
	v_cvt_pk_bf16_f32 v21, v21, s0
	v_cvt_pk_bf16_f32 v22, v22, s0
	v_cvt_pk_bf16_f32 v13, v12, v13
	v_cvt_pk_bf16_f32 v25, v25, s0
	v_perm_b32 v2, v3, v19, s34
	v_alignbit_b32 v3, v23, v3, 16
	v_perm_b32 v4, v5, v24, s34
	v_alignbit_b32 v5, v27, v5, 16
	v_perm_b32 v6, v7, v28, s34
	v_alignbit_b32 v7, v31, v7, 16
	v_perm_b32 v8, v9, v14, s34
	v_alignbit_b32 v9, v17, v9, 16
	v_perm_b32 v10, v11, v18, s34
	v_alignbit_b32 v11, v21, v11, 16
	v_perm_b32 v12, v13, v22, s34
	v_alignbit_b32 v13, v25, v13, 16
	ds_write2_b64 v20, v[2:3], v[4:5] offset1:2
	ds_write2_b64 v20, v[6:7], v[8:9] offset0:4 offset1:6
	ds_write2_b64 v20, v[10:11], v[12:13] offset0:8 offset1:10
	v_pk_mul_f32 v[2:3], v[36:37], v[0:1] op_sel_hi:[1,0]
	v_mul_f32_e32 v26, v26, v0
	v_cvt_pk_bf16_f32 v2, v2, v3
	v_mul_f32_e32 v3, v29, v0
	v_cvt_pk_bf16_f32 v26, v26, s0
	v_cvt_pk_bf16_f32 v3, v3, s0
	v_perm_b32 v6, v2, v26, s34
	v_alignbit_b32 v7, v3, v2, 16
	v_mul_f32_e32 v2, v30, v0
	v_pk_mul_f32 v[8:9], v[34:35], v[0:1] op_sel_hi:[1,0]
	v_mul_f32_e32 v0, v33, v0
	v_cvt_pk_bf16_f32 v10, v2, s0
	v_cvt_pk_bf16_f32 v9, v8, v9
	v_cvt_pk_bf16_f32 v0, v0, s0
	v_perm_b32 v8, v9, v10, s34
	v_alignbit_b32 v9, v0, v9, 16
	v_lshl_or_b32 v0, v16, 1, s14
	ds_write2_b64 v20, v[6:7], v[8:9] offset0:12 offset1:14
	v_mad_u32_u24 v0, v15, s28, v0
	ds_read_b128 v[6:9], v0
	ds_read_b128 v[10:13], v0 offset:1152
	v_or_b32_e32 v2, 16, v52
	v_mov_b32_e32 v3, s17
	v_lshlrev_b64 v[2:3], 10, v[2:3]
	v_lshl_add_u64 v[2:3], v[2:3], 0, v[50:51]
	v_lshlrev_b64 v[18:19], 1, v[2:3]
	v_lshl_add_u64 v[2:3], s[10:11], 0, v[18:19]
	s_waitcnt vmcnt(1)
	v_and_b32_e32 v14, 0xffff0000, v57
	s_waitcnt lgkmcnt(1)
	v_and_b32_e32 v15, 0xffff0000, v9
	v_mov_b32_e32 v2, v168
	v_mov_b32_e32 v3, v169
	v_mov_b32_e32 v4, v170
	v_mov_b32_e32 v5, v171
	v_mul_f32_e32 v14, v15, v14
	v_lshlrev_b32_e32 v15, 16, v57
	v_lshlrev_b32_e32 v9, 16, v9
	v_mul_f32_e32 v9, v9, v15
	v_cvt_pk_bf16_f32 v9, v9, v14
	v_and_b32_e32 v14, 0xffff0000, v56
	v_and_b32_e32 v15, 0xffff0000, v8
	v_mul_f32_e32 v14, v15, v14
	v_lshlrev_b32_e32 v15, 16, v56
	v_lshlrev_b32_e32 v8, 16, v8
	v_mul_f32_e32 v8, v8, v15
	v_or_b32_e32 v52, 24, v52
	v_cvt_pk_bf16_f32 v8, v8, v14
	v_lshlrev_b64 v[14:15], 10, v[52:53]
	v_lshl_add_u64 v[14:15], v[14:15], 0, v[50:51]
	v_lshlrev_b64 v[20:21], 1, v[14:15]
	v_lshl_add_u64 v[14:15], s[10:11], 0, v[20:21]
	v_mov_b32_e32 v14, v172
	v_mov_b32_e32 v15, v173
	v_mov_b32_e32 v16, v174
	v_mov_b32_e32 v17, v175
	v_and_b32_e32 v22, 0xffff0000, v55
	v_and_b32_e32 v23, 0xffff0000, v7
	v_mul_f32_e32 v22, v23, v22
	v_lshlrev_b32_e32 v23, 16, v55
	v_lshlrev_b32_e32 v7, 16, v7
	v_mul_f32_e32 v7, v7, v23
	v_cvt_pk_bf16_f32 v7, v7, v22
	v_and_b32_e32 v22, 0xffff0000, v54
	v_and_b32_e32 v23, 0xffff0000, v6
	v_mul_f32_e32 v22, v23, v22
	v_lshlrev_b32_e32 v23, 16, v54
	v_lshlrev_b32_e32 v6, 16, v6
	v_mul_f32_e32 v6, v6, v23
	v_cvt_pk_bf16_f32 v6, v6, v22
	v_lshl_add_u64 v[22:23], s[8:9], 0, v[62:63]
	global_store_dwordx4 v[22:23], v[6:9], off
	v_lshl_add_u64 v[22:23], s[8:9], 0, v[66:67]
	s_waitcnt vmcnt(3)
	v_and_b32_e32 v6, 0xffff0000, v61
	s_waitcnt lgkmcnt(0)
	v_and_b32_e32 v7, 0xffff0000, v13
	v_mul_f32_e32 v6, v7, v6
	v_lshlrev_b32_e32 v7, 16, v61
	v_lshlrev_b32_e32 v8, 16, v13
	v_mul_f32_e32 v7, v8, v7
	v_cvt_pk_bf16_f32 v9, v7, v6
	v_and_b32_e32 v6, 0xffff0000, v60
	v_and_b32_e32 v7, 0xffff0000, v12
	v_mul_f32_e32 v6, v7, v6
	v_lshlrev_b32_e32 v7, 16, v60
	v_lshlrev_b32_e32 v8, 16, v12
	v_mul_f32_e32 v7, v8, v7
	v_cvt_pk_bf16_f32 v8, v7, v6
	v_and_b32_e32 v6, 0xffff0000, v59
	v_and_b32_e32 v7, 0xffff0000, v11
	v_mul_f32_e32 v6, v7, v6
	v_lshlrev_b32_e32 v7, 16, v59
	v_lshlrev_b32_e32 v11, 16, v11
	v_mul_f32_e32 v7, v11, v7
	v_cvt_pk_bf16_f32 v7, v7, v6
	v_and_b32_e32 v6, 0xffff0000, v58
	v_and_b32_e32 v11, 0xffff0000, v10
	v_mul_f32_e32 v6, v11, v6
	v_lshlrev_b32_e32 v11, 16, v58
	v_lshlrev_b32_e32 v10, 16, v10
	v_mul_f32_e32 v10, v10, v11
	v_cvt_pk_bf16_f32 v6, v10, v6
	ds_read_b128 v[10:13], v0 offset:2304
	global_store_dwordx4 v[22:23], v[6:9], off
	ds_read_b128 v[6:9], v0 offset:3456
	s_waitcnt lgkmcnt(1)
	v_and_b32_e32 v0, 0xffff0000, v13
	v_lshlrev_b32_e32 v13, 16, v13
	s_waitcnt vmcnt(3)
	v_and_b32_e32 v22, 0xffff0000, v5
	v_lshlrev_b32_e32 v5, 16, v5
	v_mul_f32_e32 v0, v0, v22
	v_mul_f32_e32 v5, v13, v5
	v_cvt_pk_bf16_f32 v5, v5, v0
	v_and_b32_e32 v0, 0xffff0000, v4
	v_and_b32_e32 v13, 0xffff0000, v12
	v_lshlrev_b32_e32 v4, 16, v4
	v_lshlrev_b32_e32 v12, 16, v12
	v_mul_f32_e32 v0, v13, v0
	v_mul_f32_e32 v4, v12, v4
	v_cvt_pk_bf16_f32 v4, v4, v0
	v_and_b32_e32 v0, 0xffff0000, v3
	v_and_b32_e32 v12, 0xffff0000, v11
	v_lshlrev_b32_e32 v3, 16, v3
	v_lshlrev_b32_e32 v11, 16, v11
	v_mul_f32_e32 v0, v12, v0
	v_mul_f32_e32 v3, v11, v3
	v_cvt_pk_bf16_f32 v3, v3, v0
	v_and_b32_e32 v0, 0xffff0000, v2
	v_and_b32_e32 v11, 0xffff0000, v10
	v_lshlrev_b32_e32 v2, 16, v2
	v_lshlrev_b32_e32 v10, 16, v10
	v_mul_f32_e32 v0, v11, v0
	v_mul_f32_e32 v2, v10, v2
	v_cvt_pk_bf16_f32 v2, v2, v0
	v_lshl_add_u64 v[10:11], s[8:9], 0, v[18:19]
	global_store_dwordx4 v[10:11], v[2:5], off
	s_waitcnt lgkmcnt(0)
	v_and_b32_e32 v0, 0xffff0000, v9
	s_waitcnt vmcnt(3)
	v_and_b32_e32 v2, 0xffff0000, v17
	v_mul_f32_e32 v0, v0, v2
	v_lshlrev_b32_e32 v2, 16, v9
	v_lshlrev_b32_e32 v3, 16, v17
	v_mul_f32_e32 v2, v2, v3
	v_cvt_pk_bf16_f32 v5, v2, v0
	v_and_b32_e32 v0, 0xffff0000, v8
	v_and_b32_e32 v2, 0xffff0000, v16
	v_mul_f32_e32 v0, v0, v2
	v_lshlrev_b32_e32 v2, 16, v8
	v_lshlrev_b32_e32 v3, 16, v16
	v_mul_f32_e32 v2, v2, v3
	v_cvt_pk_bf16_f32 v4, v2, v0
	v_and_b32_e32 v0, 0xffff0000, v7
	v_and_b32_e32 v2, 0xffff0000, v15
	v_mul_f32_e32 v0, v0, v2
	v_lshlrev_b32_e32 v2, 16, v7
	v_lshlrev_b32_e32 v3, 16, v15
	v_mul_f32_e32 v2, v2, v3
	v_cvt_pk_bf16_f32 v3, v2, v0
	v_and_b32_e32 v0, 0xffff0000, v6
	v_and_b32_e32 v2, 0xffff0000, v14
	v_mul_f32_e32 v0, v0, v2
	v_lshlrev_b32_e32 v2, 16, v6
	v_lshlrev_b32_e32 v6, 16, v14
	v_mul_f32_e32 v2, v2, v6
	v_cvt_pk_bf16_f32 v2, v2, v0
	v_lshl_add_u64 v[6:7], s[8:9], 0, v[20:21]
	global_store_dwordx4 v[6:7], v[2:5], off
	s_cbranch_scc0 .LBB0_2157
.LBB0_2137:
	s_bfe_u32 s10, s24, 0x10007
	s_lshl_b32 s9, s10, 3
	s_ashr_i32 s8, s24, 8
	s_add_i32 s20, s9, s25
	s_lshl_b32 s9, s24, 5
	s_and_b32 s21, s9, 0xfe0
	s_ashr_i32 s9, s8, 31
	s_lshl_b64 s[16:17], s[8:9], 12
	s_or_b32 s16, s16, s21
	v_mov_b32_e32 v3, s17
	v_or_b32_e32 v2, s16, v90
	v_lshlrev_b64 v[2:3], 11, v[2:3]
	s_lshl_b32 s18, s20, 6
	s_waitcnt lgkmcnt(0)
	s_lshl_b32 s84, s20, 2
	s_add_u32 s88, s82, s84
	s_addc_u32 s89, s83, 0
	global_load_dword v176, v177, s[88:89]
	s_lshl_b32 s84, s16, 11
	s_lshl_b32 s85, s18, 1
	s_add_u32 s84, s84, s85
	s_add_u32 s88, s86, s84
	s_addc_u32 s89, s87, 0
	global_load_dwordx4 v[160:163], v178, s[88:89]
	s_add_u32 s90, s88, 0x4000
	s_addc_u32 s91, s89, 0
	global_load_dwordx4 v[164:167], v178, s[90:91]
	s_add_u32 s92, s88, 0x8000
	s_addc_u32 s93, s89, 0
	global_load_dwordx4 v[168:171], v178, s[92:93]
	s_add_u32 s94, s88, 0xc000
	s_addc_u32 s95, s89, 0
	global_load_dwordx4 v[172:175], v178, s[94:95]
	v_lshl_add_u64 v[2:3], s[4:5], 0, v[2:3]
	s_ashr_i32 s19, s18, 31
	s_and_b32 s3, s26, 0xfe0
	v_lshl_add_u64 v[2:3], s[18:19], 1, v[2:3]
	v_sub_u32_e64 v0, s3, v99 clamp
	v_lshl_add_u64 v[2:3], v[2:3], 0, v[92:93]
	v_readfirstlane_b32 s2, v0
	global_load_dwordx4 v[74:77], v[2:3], off
	global_load_dwordx4 v[78:81], v[2:3], off offset:32
	global_load_dwordx4 v[82:85], v[2:3], off offset:64
	global_load_dwordx4 v[86:89], v[2:3], off offset:96
	v_mov_b32_e32 v2, v91
	s_lshr_b32 s2, s2, 6
	s_lshl_b64 s[8:9], s[8:9], 20
	s_add_u32 s11, s6, s8
	v_add_u32_e32 v0, s70, v2
	v_ashrrev_i32_e32 v4, 31, v0
	s_addc_u32 s14, s7, s9
	s_lshl_b32 s35, s10, 7
	v_lshrrev_b32_e32 v4, 29, v4
	s_add_u32 s10, s11, s35
	v_add_u32_e32 v5, v0, v4
	s_addc_u32 s11, s14, 0
	v_ashrrev_i32_e32 v4, 3, v5
	v_and_b32_e32 v5, 0x1ffffff8, v5
	s_add_u32 s8, s12, s8
	v_sub_u32_e32 v0, v0, v5
	s_addc_u32 s9, s13, s9
	v_lshlrev_b32_e32 v6, 3, v0
	v_ashrrev_i32_e32 v5, 31, v4
	s_add_u32 s8, s8, s35
	v_sub_u32_e64 v3, s21, v99 clamp
	v_lshlrev_b64 v[8:9], 8, v[4:5]
	v_ashrrev_i32_e32 v7, 31, v6
	s_addc_u32 s9, s9, 0
	v_lshl_add_u64 v[10:11], s[10:11], 0, v[8:9]
	v_lshlrev_b64 v[12:13], 1, v[6:7]
	v_lshlrev_b32_e32 v0, 8, v3
	v_lshl_add_u64 v[94:95], v[10:11], 0, v[12:13]
	v_lshl_add_u64 v[8:9], s[8:9], 0, v[8:9]
	v_and_b32_e32 v0, 0xfc000, v0
	v_lshl_add_u64 v[96:97], v[8:9], 0, v[12:13]
	v_lshl_add_u64 v[8:9], v[94:95], 0, v[0:1]
	global_load_dwordx4 v[66:69], v[8:9], off
	v_lshl_add_u64 v[8:9], v[96:97], 0, v[0:1]
	global_load_dwordx4 v[70:73], v[8:9], off
	v_readfirstlane_b32 s9, v3
	s_lshr_b32 s10, s9, 6
	s_add_i32 s9, s21, 0xffffff81
	s_add_i32 s8, s21, 0x5f
	s_lshr_b32 s9, s9, 6
	s_lshr_b32 s8, s8, 6
	s_max_u32 s9, s9, s10
	s_cmpk_gt_u32 s21, 0x7f
	s_cselect_b32 s9, s9, 0
	s_cmp_ge_u32 s10, s9
	v_mul_lo_u32 v102, v4, s28
	v_mul_lo_u32 v103, v4, s29
	v_lshlrev_b32_e32 v104, 1, v6
	s_waitcnt vmcnt(63) expcnt(7) lgkmcnt(15)
	s_barrier
	s_cbranch_scc1 .LBB0_2142
	s_lshl_b32 s10, s2, 6
	s_add_i32 s14, s10, 64
	s_mov_b32 s10, 0
	s_branch .LBB0_2140
